# XR epilogue: the eleven modulation / g_pre loads of the 32 context rows' hx issued together (was 8 dependent round trips)
# speedup vs baseline: 1.0028x; 1.0028x over previous
.LBB0_1185:
	s_or_b64 exec, exec, s[4:5]
	s_add_u32 s4, s54, s24
	s_addc_u32 s5, s55, s25
	s_add_u32 s24, s4, 0x1000
	s_addc_u32 s25, s5, 0
	s_lshl_b64 s[4:5], s[6:7], 1
	s_add_u32 s4, s50, s4
	s_addc_u32 s5, s51, s5
	s_add_u32 s4, s4, s22
	s_addc_u32 s5, s5, s23
	s_add_i32 s6, s38, 9
	s_mul_hi_i32 s7, s6, 0x3000
	s_mulk_i32 s6, 0x3000
	s_add_u32 s22, s36, s6
	s_addc_u32 s23, s37, s7
	s_add_u32 s6, s22, 0x1000
	s_addc_u32 s7, s23, 0
	v_lshlrev_b64 v[40:41], 2, v[200:201]
	s_waitcnt lgkmcnt(0)
	s_barrier
	v_lshl_add_u64 v[4:5], s[6:7], 0, v[158:159]
	v_lshl_add_u64 v[12:13], s[6:7], 0, v[40:41]
	global_load_dwordx4 v[4:7], v[4:5], off
	v_lshl_add_u64 v[44:45], s[24:25], 0, v[40:41]
	global_load_dwordx4 v[12:15], v[12:13], off
	v_lshlrev_b64 v[32:33], 2, v[206:207]
	global_load_dwordx4 v[8:11], v[44:45], off
	v_lshl_add_u64 v[16:17], s[6:7], 0, v[32:33]
	v_lshl_add_u64 v[42:43], s[24:25], 0, v[32:33]
	global_load_dwordx4 v[16:19], v[16:17], off
	v_lshlrev_b64 v[30:31], 2, v[208:209]
	v_lshl_add_u64 v[200:201], s[6:7], 0, v[30:31]
	v_lshl_add_u64 v[0:1], s[24:25], 0, v[158:159]
	v_lshl_add_u64 v[34:35], s[24:25], 0, v[30:31]
	global_load_dwordx4 v[206:209], v[200:201], off
	v_lshl_add_u64 v[154:155], s[22:23], 0, v[158:159]
	global_load_dwordx4 v[0:3], v[0:1], off
	ds_read_b32 v148, v220 offset:8192
	s_add_u32 s6, s36, 0x33000
	s_addc_u32 s7, s37, 0
	s_add_u32 s22, s36, 0x34000
	s_addc_u32 s23, s37, 0
	s_waitcnt lgkmcnt(0)
	v_pk_mul_f32 v[144:145], v[144:145], v[148:149] op_sel_hi:[1,0]
	v_pk_mul_f32 v[146:147], v[146:147], v[148:149] op_sel_hi:[1,0]
	v_pk_mul_f32 v[140:141], v[140:141], v[148:149] op_sel_hi:[1,0]
	v_pk_mul_f32 v[142:143], v[142:143], v[148:149] op_sel_hi:[1,0]
	v_pk_mul_f32 v[136:137], v[136:137], v[148:149] op_sel_hi:[1,0]
	v_pk_mul_f32 v[138:139], v[138:139], v[148:149] op_sel_hi:[1,0]
	v_pk_mul_f32 v[124:125], v[124:125], v[148:149] op_sel_hi:[1,0]
	v_pk_mul_f32 v[126:127], v[126:127], v[148:149] op_sel_hi:[1,0]
	v_lshlrev_b32_e32 v148, 1, v28
	s_waitcnt vmcnt(5)
	v_pk_add_f32 v[6:7], v[6:7], 1.0 op_sel_hi:[1,0]
	v_pk_add_f32 v[4:5], v[4:5], 1.0 op_sel_hi:[1,0]
	s_waitcnt vmcnt(4)
	v_pk_add_f32 v[14:15], v[14:15], 1.0 op_sel_hi:[1,0]
	v_pk_add_f32 v[12:13], v[12:13], 1.0 op_sel_hi:[1,0]
	s_waitcnt vmcnt(3)
	v_pk_mul_f32 v[192:193], v[10:11], v[14:15]
	v_pk_mul_f32 v[194:195], v[8:9], v[12:13]
	global_load_dwordx4 v[12:15], v[42:43], off
	s_waitcnt vmcnt(3)
	v_pk_add_f32 v[18:19], v[18:19], 1.0 op_sel_hi:[1,0]
	v_pk_add_f32 v[16:17], v[16:17], 1.0 op_sel_hi:[1,0]
	global_load_dwordx4 v[8:11], v[154:155], off offset:64
	s_waitcnt vmcnt(3)
	v_pk_add_f32 v[200:201], v[208:209], 1.0 op_sel_hi:[1,0]
	v_pk_add_f32 v[206:207], v[206:207], 1.0 op_sel_hi:[1,0]
	s_waitcnt vmcnt(2)
	v_pk_mul_f32 v[160:161], v[2:3], v[6:7]
	v_pk_mul_f32 v[162:163], v[0:1], v[4:5]
	global_load_dwordx4 v[4:7], v[154:155], off
	s_waitcnt vmcnt(2)
	v_pk_mul_f32 v[196:197], v[14:15], v[18:19]
	v_pk_mul_f32 v[198:199], v[12:13], v[16:17]
	global_load_dwordx4 v[16:19], v[34:35], off
	global_load_dwordx4 v[12:15], v[154:155], off offset:512
	s_waitcnt vmcnt(3)
	v_pk_fma_f32 v[140:141], v[192:193], v[140:141], v[10:11]
	v_pk_fma_f32 v[142:143], v[194:195], v[142:143], v[8:9]
	s_waitcnt vmcnt(2)
	v_pk_fma_f32 v[144:145], v[160:161], v[144:145], v[6:7]
	v_pk_fma_f32 v[146:147], v[162:163], v[146:147], v[4:5]
	v_cvt_pk_bf16_f32 v142, v142, v143
	v_cvt_pk_bf16_f32 v146, v146, v147
	v_cvt_pk_bf16_f32 v147, v144, v145
	v_cvt_pk_bf16_f32 v143, v140, v141
	ds_write_b64 v223, v[146:147] offset:10240
	ds_write_b64 v224, v[142:143] offset:10240
	s_waitcnt vmcnt(1)
	v_pk_mul_f32 v[200:201], v[18:19], v[200:201]
	v_pk_mul_f32 v[206:207], v[16:17], v[206:207]
	global_load_dwordx4 v[16:19], v[154:155], off offset:576
	s_waitcnt vmcnt(1)
	v_pk_fma_f32 v[136:137], v[196:197], v[136:137], v[14:15]
	v_pk_fma_f32 v[138:139], v[198:199], v[138:139], v[12:13]
	s_waitcnt vmcnt(0)
	v_pk_fma_f32 v[124:125], v[200:201], v[124:125], v[18:19]
	v_pk_fma_f32 v[126:127], v[206:207], v[126:127], v[16:17]
	v_cvt_pk_bf16_f32 v138, v138, v139
	v_cvt_pk_bf16_f32 v139, v136, v137
	v_cvt_pk_bf16_f32 v126, v126, v127
	v_cvt_pk_bf16_f32 v127, v124, v125
	ds_write_b64 v225, v[138:139] offset:10240
	ds_write_b64 v226, v[126:127] offset:10240
	ds_read_b32 v124, v220 offset:8256
	s_waitcnt lgkmcnt(0)
	v_pk_mul_f32 v[126:127], v[132:133], v[124:125] op_sel_hi:[1,0]
	v_pk_mul_f32 v[132:133], v[134:135], v[124:125] op_sel_hi:[1,0]
	v_pk_fma_f32 v[126:127], v[160:161], v[126:127], v[6:7]
	v_pk_fma_f32 v[132:133], v[162:163], v[132:133], v[4:5]
	v_pk_mul_f32 v[116:117], v[116:117], v[124:125] op_sel_hi:[1,0]
	v_cvt_pk_bf16_f32 v132, v132, v133
	v_cvt_pk_bf16_f32 v133, v126, v127
	v_pk_mul_f32 v[126:127], v[128:129], v[124:125] op_sel_hi:[1,0]
	v_pk_mul_f32 v[128:129], v[130:131], v[124:125] op_sel_hi:[1,0]
	v_pk_mul_f32 v[118:119], v[118:119], v[124:125] op_sel_hi:[1,0]
	v_pk_mul_f32 v[108:109], v[108:109], v[124:125] op_sel_hi:[1,0]
	v_pk_mul_f32 v[110:111], v[110:111], v[124:125] op_sel_hi:[1,0]
	v_pk_fma_f32 v[126:127], v[192:193], v[126:127], v[10:11]
	v_pk_fma_f32 v[128:129], v[194:195], v[128:129], v[8:9]
	v_pk_fma_f32 v[116:117], v[196:197], v[116:117], v[14:15]
	v_pk_fma_f32 v[118:119], v[198:199], v[118:119], v[12:13]
	v_pk_fma_f32 v[108:109], v[200:201], v[108:109], v[18:19]
	v_pk_fma_f32 v[110:111], v[206:207], v[110:111], v[16:17]
	v_cvt_pk_bf16_f32 v128, v128, v129
	v_cvt_pk_bf16_f32 v129, v126, v127
	v_cvt_pk_bf16_f32 v118, v118, v119
	v_cvt_pk_bf16_f32 v119, v116, v117
	v_cvt_pk_bf16_f32 v110, v110, v111
	v_cvt_pk_bf16_f32 v111, v108, v109
	ds_write_b64 v227, v[132:133] offset:10240
	ds_write_b64 v228, v[128:129] offset:10240
	ds_write_b64 v229, v[118:119] offset:10240
	ds_write_b64 v230, v[110:111] offset:10240
	ds_read_b32 v108, v220 offset:8320
	s_waitcnt lgkmcnt(0)
	v_pk_mul_f32 v[110:111], v[120:121], v[108:109] op_sel_hi:[1,0]
	v_pk_mul_f32 v[116:117], v[122:123], v[108:109] op_sel_hi:[1,0]
	v_pk_fma_f32 v[110:111], v[160:161], v[110:111], v[6:7]
	v_pk_fma_f32 v[116:117], v[162:163], v[116:117], v[4:5]
	v_pk_mul_f32 v[100:101], v[100:101], v[108:109] op_sel_hi:[1,0]
	v_cvt_pk_bf16_f32 v116, v116, v117
	v_cvt_pk_bf16_f32 v117, v110, v111
	v_pk_mul_f32 v[110:111], v[112:113], v[108:109] op_sel_hi:[1,0]
	v_pk_mul_f32 v[112:113], v[114:115], v[108:109] op_sel_hi:[1,0]
	v_pk_mul_f32 v[102:103], v[102:103], v[108:109] op_sel_hi:[1,0]
	v_pk_mul_f32 v[92:93], v[92:93], v[108:109] op_sel_hi:[1,0]
	v_pk_mul_f32 v[94:95], v[94:95], v[108:109] op_sel_hi:[1,0]
	v_pk_fma_f32 v[110:111], v[192:193], v[110:111], v[10:11]
	v_pk_fma_f32 v[112:113], v[194:195], v[112:113], v[8:9]
	v_pk_fma_f32 v[100:101], v[196:197], v[100:101], v[14:15]
	v_pk_fma_f32 v[102:103], v[198:199], v[102:103], v[12:13]
	v_pk_fma_f32 v[92:93], v[200:201], v[92:93], v[18:19]
	v_pk_fma_f32 v[94:95], v[206:207], v[94:95], v[16:17]
	v_cvt_pk_bf16_f32 v112, v112, v113
	v_cvt_pk_bf16_f32 v113, v110, v111
	v_cvt_pk_bf16_f32 v102, v102, v103
	v_cvt_pk_bf16_f32 v103, v100, v101
	v_cvt_pk_bf16_f32 v94, v94, v95
	v_cvt_pk_bf16_f32 v95, v92, v93
	ds_write_b64 v231, v[116:117] offset:10240
	ds_write_b64 v232, v[112:113] offset:10240
	ds_write_b64 v233, v[102:103] offset:10240
	ds_write_b64 v234, v[94:95] offset:10240
	ds_read_b32 v92, v220 offset:8384
	s_waitcnt lgkmcnt(0)
	v_pk_mul_f32 v[94:95], v[104:105], v[92:93] op_sel_hi:[1,0]
	v_pk_mul_f32 v[100:101], v[106:107], v[92:93] op_sel_hi:[1,0]
	v_pk_fma_f32 v[94:95], v[160:161], v[94:95], v[6:7]
	v_pk_fma_f32 v[100:101], v[162:163], v[100:101], v[4:5]
	v_pk_mul_f32 v[88:89], v[88:89], v[92:93] op_sel_hi:[1,0]
	v_cvt_pk_bf16_f32 v100, v100, v101
	v_cvt_pk_bf16_f32 v101, v94, v95
	v_pk_mul_f32 v[94:95], v[96:97], v[92:93] op_sel_hi:[1,0]
	v_pk_mul_f32 v[96:97], v[98:99], v[92:93] op_sel_hi:[1,0]
	v_pk_mul_f32 v[90:91], v[90:91], v[92:93] op_sel_hi:[1,0]
	v_pk_mul_f32 v[84:85], v[84:85], v[92:93] op_sel_hi:[1,0]
	v_pk_mul_f32 v[86:87], v[86:87], v[92:93] op_sel_hi:[1,0]
	v_pk_fma_f32 v[94:95], v[192:193], v[94:95], v[10:11]
	v_pk_fma_f32 v[96:97], v[194:195], v[96:97], v[8:9]
	v_pk_fma_f32 v[88:89], v[196:197], v[88:89], v[14:15]
	v_pk_fma_f32 v[90:91], v[198:199], v[90:91], v[12:13]
	v_pk_fma_f32 v[84:85], v[200:201], v[84:85], v[18:19]
	v_pk_fma_f32 v[86:87], v[206:207], v[86:87], v[16:17]
	v_cvt_pk_bf16_f32 v96, v96, v97
	v_cvt_pk_bf16_f32 v97, v94, v95
	v_cvt_pk_bf16_f32 v90, v90, v91
	v_cvt_pk_bf16_f32 v91, v88, v89
	v_cvt_pk_bf16_f32 v86, v86, v87
	v_cvt_pk_bf16_f32 v87, v84, v85
	ds_write_b64 v235, v[100:101] offset:10240
	ds_write_b64 v236, v[96:97] offset:10240
	ds_write_b64 v237, v[90:91] offset:10240
	ds_write_b64 v238, v[86:87] offset:10240
	ds_read_b32 v84, v220 offset:8704
	s_waitcnt lgkmcnt(0)
	v_pk_mul_f32 v[80:81], v[80:81], v[84:85] op_sel_hi:[1,0]
	v_pk_mul_f32 v[82:83], v[82:83], v[84:85] op_sel_hi:[1,0]
	v_pk_mul_f32 v[76:77], v[76:77], v[84:85] op_sel_hi:[1,0]
	v_pk_mul_f32 v[78:79], v[78:79], v[84:85] op_sel_hi:[1,0]
	v_pk_mul_f32 v[68:69], v[68:69], v[84:85] op_sel_hi:[1,0]
	v_pk_mul_f32 v[70:71], v[70:71], v[84:85] op_sel_hi:[1,0]
	v_pk_mul_f32 v[60:61], v[60:61], v[84:85] op_sel_hi:[1,0]
	v_pk_mul_f32 v[62:63], v[62:63], v[84:85] op_sel_hi:[1,0]
	v_pk_fma_f32 v[80:81], v[160:161], v[80:81], v[6:7]
	v_pk_fma_f32 v[82:83], v[162:163], v[82:83], v[4:5]
	v_pk_fma_f32 v[76:77], v[192:193], v[76:77], v[10:11]
	v_pk_fma_f32 v[78:79], v[194:195], v[78:79], v[8:9]
	v_pk_fma_f32 v[68:69], v[196:197], v[68:69], v[14:15]
	v_pk_fma_f32 v[70:71], v[198:199], v[70:71], v[12:13]
	v_pk_fma_f32 v[60:61], v[200:201], v[60:61], v[18:19]
	v_pk_fma_f32 v[62:63], v[206:207], v[62:63], v[16:17]
	v_cvt_pk_bf16_f32 v82, v82, v83
	v_cvt_pk_bf16_f32 v83, v80, v81
	v_cvt_pk_bf16_f32 v78, v78, v79
	v_cvt_pk_bf16_f32 v79, v76, v77
	v_cvt_pk_bf16_f32 v70, v70, v71
	v_cvt_pk_bf16_f32 v71, v68, v69
	v_cvt_pk_bf16_f32 v62, v62, v63
	v_cvt_pk_bf16_f32 v63, v60, v61
	ds_write_b64 v239, v[82:83] offset:10240
	ds_write_b64 v240, v[78:79] offset:10240
	ds_write_b64 v241, v[70:71] offset:10240
	ds_write_b64 v242, v[62:63] offset:10240
	ds_read_b32 v60, v220 offset:8768
	s_waitcnt lgkmcnt(0)
	v_pk_mul_f32 v[52:53], v[52:53], v[60:61] op_sel_hi:[1,0]
	v_pk_mul_f32 v[54:55], v[54:55], v[60:61] op_sel_hi:[1,0]
	v_pk_mul_f32 v[62:63], v[72:73], v[60:61] op_sel_hi:[1,0]
	v_pk_mul_f32 v[68:69], v[74:75], v[60:61] op_sel_hi:[1,0]
	v_pk_fma_f32 v[52:53], v[196:197], v[52:53], v[14:15]
	v_pk_fma_f32 v[54:55], v[198:199], v[54:55], v[12:13]
	v_pk_fma_f32 v[62:63], v[160:161], v[62:63], v[6:7]
	v_pk_fma_f32 v[68:69], v[162:163], v[68:69], v[4:5]
	v_cvt_pk_bf16_f32 v54, v54, v55
	v_cvt_pk_bf16_f32 v55, v52, v53
	v_cvt_pk_bf16_f32 v68, v68, v69
	v_cvt_pk_bf16_f32 v69, v62, v63
	v_pk_mul_f32 v[62:63], v[64:65], v[60:61] op_sel_hi:[1,0]
	v_pk_mul_f32 v[64:65], v[66:67], v[60:61] op_sel_hi:[1,0]
	ds_write_b64 v245, v[54:55] offset:10240
	v_pk_mul_f32 v[52:53], v[164:165], v[60:61] op_sel_hi:[1,0]
	v_pk_mul_f32 v[54:55], v[166:167], v[60:61] op_sel_hi:[1,0]
	v_pk_fma_f32 v[62:63], v[192:193], v[62:63], v[10:11]
	v_pk_fma_f32 v[64:65], v[194:195], v[64:65], v[8:9]
	v_pk_fma_f32 v[52:53], v[200:201], v[52:53], v[18:19]
	v_pk_fma_f32 v[54:55], v[206:207], v[54:55], v[16:17]
	v_cvt_pk_bf16_f32 v64, v64, v65
	v_cvt_pk_bf16_f32 v65, v62, v63
	v_cvt_pk_bf16_f32 v54, v54, v55
	v_cvt_pk_bf16_f32 v55, v52, v53
	ds_write_b64 v243, v[68:69] offset:10240
	ds_write_b64 v244, v[64:65] offset:10240
	ds_write_b64 v246, v[54:55] offset:10240
	ds_read_b32 v52, v220 offset:8832
	s_waitcnt lgkmcnt(0)
	v_pk_mul_f32 v[48:49], v[48:49], v[52:53] op_sel_hi:[1,0]
	v_pk_mul_f32 v[50:51], v[50:51], v[52:53] op_sel_hi:[1,0]
	v_pk_fma_f32 v[48:49], v[192:193], v[48:49], v[10:11]
	v_pk_fma_f32 v[50:51], v[194:195], v[50:51], v[8:9]
	v_pk_mul_f32 v[54:55], v[56:57], v[52:53] op_sel_hi:[1,0]
	v_cvt_pk_bf16_f32 v50, v50, v51
	v_cvt_pk_bf16_f32 v51, v48, v49
	ds_write_b64 v248, v[50:51] offset:10240
	v_pk_mul_f32 v[48:49], v[168:169], v[52:53] op_sel_hi:[1,0]
	v_pk_mul_f32 v[50:51], v[170:171], v[52:53] op_sel_hi:[1,0]
	v_pk_fma_f32 v[48:49], v[196:197], v[48:49], v[14:15]
	v_pk_fma_f32 v[50:51], v[198:199], v[50:51], v[12:13]
	v_pk_mul_f32 v[56:57], v[58:59], v[52:53] op_sel_hi:[1,0]
	v_cvt_pk_bf16_f32 v50, v50, v51
	v_cvt_pk_bf16_f32 v51, v48, v49
	ds_write_b64 v249, v[50:51] offset:10240
	v_pk_mul_f32 v[48:49], v[172:173], v[52:53] op_sel_hi:[1,0]
	v_pk_mul_f32 v[50:51], v[174:175], v[52:53] op_sel_hi:[1,0]
	v_pk_fma_f32 v[54:55], v[160:161], v[54:55], v[6:7]
	v_pk_fma_f32 v[56:57], v[162:163], v[56:57], v[4:5]
	v_pk_fma_f32 v[48:49], v[200:201], v[48:49], v[18:19]
	v_pk_fma_f32 v[50:51], v[206:207], v[50:51], v[16:17]
	v_cvt_pk_bf16_f32 v56, v56, v57
	v_cvt_pk_bf16_f32 v57, v54, v55
	v_cvt_pk_bf16_f32 v50, v50, v51
	v_cvt_pk_bf16_f32 v51, v48, v49
	ds_write_b64 v247, v[56:57] offset:10240
	ds_write_b64 v250, v[50:51] offset:10240
	ds_read_b32 v48, v220 offset:8896
	s_waitcnt lgkmcnt(0)
	v_pk_mul_f32 v[50:51], v[176:177], v[48:49] op_sel_hi:[1,0]
	v_pk_mul_f32 v[52:53], v[178:179], v[48:49] op_sel_hi:[1,0]
	v_pk_fma_f32 v[6:7], v[160:161], v[50:51], v[6:7]
	v_pk_fma_f32 v[4:5], v[162:163], v[52:53], v[4:5]
	s_nop 0
	v_cvt_pk_bf16_f32 v4, v4, v5
	v_cvt_pk_bf16_f32 v5, v6, v7
	v_pk_mul_f32 v[6:7], v[182:183], v[48:49] op_sel_hi:[1,0]
	ds_write_b64 v251, v[4:5] offset:10240
	v_pk_mul_f32 v[4:5], v[180:181], v[48:49] op_sel_hi:[1,0]
	v_pk_fma_f32 v[6:7], v[194:195], v[6:7], v[8:9]
	v_lshl_add_u64 v[108:109], s[22:23], 0, v[158:159]
	global_load_dwordx4 v[60:63], v[108:109], off
	v_lshl_add_u64 v[110:111], s[6:7], 0, v[158:159]
	global_load_dwordx4 v[64:67], v[110:111], off
	v_lshl_add_u64 v[112:113], s[22:23], 0, v[40:41]
	global_load_dwordx4 v[68:71], v[112:113], off
	global_load_dwordx4 v[72:75], v[44:45], off
	v_lshl_add_u64 v[114:115], s[6:7], 0, v[40:41]
	global_load_dwordx4 v[76:79], v[114:115], off
	v_lshl_add_u64 v[116:117], s[22:23], 0, v[32:33]
	global_load_dwordx4 v[80:83], v[116:117], off
	global_load_dwordx4 v[84:87], v[42:43], off
	v_lshl_add_u64 v[118:119], s[6:7], 0, v[32:33]
	global_load_dwordx4 v[88:91], v[118:119], off
	v_lshl_add_u64 v[120:121], s[22:23], 0, v[30:31]
	global_load_dwordx4 v[92:95], v[120:121], off
	global_load_dwordx4 v[96:99], v[34:35], off
	v_lshl_add_u64 v[122:123], s[6:7], 0, v[30:31]
	global_load_dwordx4 v[100:103], v[122:123], off
	v_pk_fma_f32 v[4:5], v[192:193], v[4:5], v[10:11]
	v_cvt_pk_bf16_f32 v6, v6, v7
	v_cvt_pk_bf16_f32 v7, v4, v5
	ds_write_b64 v211, v[6:7] offset:10240
	v_pk_mul_f32 v[6:7], v[186:187], v[48:49] op_sel_hi:[1, 0]
	v_pk_mul_f32 v[4:5], v[184:185], v[48:49] op_sel_hi:[1, 0]
	v_pk_fma_f32 v[6:7], v[198:199], v[6:7], v[12:13]
	v_pk_fma_f32 v[4:5], v[196:197], v[4:5], v[14:15]
	v_cvt_pk_bf16_f32 v6, v6, v7
	v_cvt_pk_bf16_f32 v7, v4, v5
	ds_write_b64 v212, v[6:7] offset:10240
	v_pk_mul_f32 v[4:5], v[188:189], v[48:49] op_sel_hi:[1, 0]
	v_pk_mul_f32 v[6:7], v[190:191], v[48:49] op_sel_hi:[1, 0]
	v_pk_fma_f32 v[4:5], v[200:201], v[4:5], v[18:19]
	v_pk_fma_f32 v[6:7], v[206:207], v[6:7], v[16:17]
	s_waitcnt vmcnt(10)
	v_pk_add_f32 v[10:11], v[62:63], 1.0 op_sel_hi:[1, 0]
	v_pk_add_f32 v[12:13], v[60:61], 1.0 op_sel_hi:[1, 0]
	v_pk_mul_f32 v[8:9], v[2:3], v[10:11]
	v_pk_mul_f32 v[10:11], v[0:1], v[12:13]
	v_cvt_pk_bf16_f32 v6, v6, v7
	v_cvt_pk_bf16_f32 v7, v4, v5
	ds_write_b64 v213, v[6:7] offset:10240
	ds_read_b32 v6, v219 offset:9216
	v_lshl_add_u64 v[4:5], v[46:47], 1, s[50:51]
	v_lshl_add_u64 v[4:5], v[156:157], 1, v[4:5]
	s_waitcnt lgkmcnt(0)
	v_pk_mul_f32 v[12:13], v[202:203], v[6:7] op_sel_hi:[1, 0]
	v_pk_mul_f32 v[14:15], v[204:205], v[6:7] op_sel_hi:[1, 0]
	s_waitcnt vmcnt(9)
	v_pk_fma_f32 v[2:3], v[8:9], v[12:13], v[66:67]
	v_pk_fma_f32 v[0:1], v[10:11], v[14:15], v[64:65]
	v_cvt_pk_bf16_f32 v0, v0, v1
	v_cvt_pk_bf16_f32 v1, v2, v3
	global_store_dwordx2 v[4:5], v[0:1], off
	v_pk_mul_f32 v[12:13], v[36:37], v[6:7] op_sel_hi:[1, 0]
	v_pk_mul_f32 v[14:15], v[38:39], v[6:7] op_sel_hi:[1, 0]
	s_waitcnt vmcnt(9)
	v_pk_add_f32 v[8:9], v[68:69], 1.0 op_sel_hi:[1, 0]
	v_pk_add_f32 v[10:11], v[70:71], 1.0 op_sel_hi:[1, 0]
	s_waitcnt vmcnt(8)
	v_pk_mul_f32 v[8:9], v[72:73], v[8:9]
	v_pk_mul_f32 v[10:11], v[74:75], v[10:11]
	s_waitcnt vmcnt(7)
	v_pk_fma_f32 v[2:3], v[12:13], v[10:11], v[78:79]
	v_pk_fma_f32 v[0:1], v[14:15], v[8:9], v[76:77]
	v_cvt_pk_bf16_f32 v0, v0, v1
	v_cvt_pk_bf16_f32 v1, v2, v3
	global_store_dwordx2 v[4:5], v[0:1], off offset:32
	v_pk_mul_f32 v[12:13], v[24:25], v[6:7] op_sel_hi:[1, 0]
	v_pk_mul_f32 v[14:15], v[26:27], v[6:7] op_sel_hi:[1, 0]
	s_waitcnt vmcnt(7)
	v_pk_add_f32 v[8:9], v[80:81], 1.0 op_sel_hi:[1, 0]
	v_pk_add_f32 v[10:11], v[82:83], 1.0 op_sel_hi:[1, 0]
	s_waitcnt vmcnt(6)
	v_pk_mul_f32 v[8:9], v[84:85], v[8:9]
	v_pk_mul_f32 v[10:11], v[86:87], v[10:11]
	s_waitcnt vmcnt(5)
	v_pk_fma_f32 v[2:3], v[12:13], v[10:11], v[90:91]
	v_pk_fma_f32 v[0:1], v[14:15], v[8:9], v[88:89]
	v_cvt_pk_bf16_f32 v0, v0, v1
	v_cvt_pk_bf16_f32 v1, v2, v3
	global_store_dwordx2 v[4:5], v[0:1], off offset:256
	v_pk_mul_f32 v[12:13], v[20:21], v[6:7] op_sel_hi:[1, 0]
	v_pk_mul_f32 v[6:7], v[22:23], v[6:7] op_sel_hi:[1, 0]
	s_waitcnt vmcnt(5)
	v_pk_add_f32 v[8:9], v[92:93], 1.0 op_sel_hi:[1, 0]
	v_pk_add_f32 v[10:11], v[94:95], 1.0 op_sel_hi:[1, 0]
	s_waitcnt vmcnt(4)
	v_pk_mul_f32 v[8:9], v[96:97], v[8:9]
	v_pk_mul_f32 v[10:11], v[98:99], v[10:11]
	s_waitcnt vmcnt(3)
	v_pk_fma_f32 v[2:3], v[12:13], v[10:11], v[102:103]
	v_pk_fma_f32 v[0:1], v[6:7], v[8:9], v[100:101]
	s_nop 0
	v_cvt_pk_bf16_f32 v0, v0, v1
	v_cvt_pk_bf16_f32 v1, v2, v3
	global_store_dwordx2 v[4:5], v[0:1], off offset:288
	s_waitcnt lgkmcnt(0)
	s_barrier
	v_lshl_add_u64 v[0:1], s[4:5], 0, v[148:149]
	s_mov_b32 s4, 0
